# v5_hoist2_nt
# baseline (speedup 1.0000x reference)
; #define STAGE(PP, RSRC, br, kt) do { const int _so = ((br) * K + (kt) * BK) * 2; \
;       __builtin_amdgcn_raw_ptr_buffer_load_lds(RSRC, LDSP((char*)(PP) + ldsoff), 16, voff0, _so, 0, 0); \
;       __builtin_amdgcn_raw_ptr_buffer_load_lds(RSRC, LDSP((char*)(PP) + ldsoff + 8192), 16, voff1, _so, 0, 0); \
;     } while (0)
; #define BAR __builtin_amdgcn_s_barrier()
; __device__ __forceinline__ void gemm_tile(const Params& P, const GArgs& ga, const TileDesc& td, int wid_s) {
;     ...
;   STAGE(SB(0, 0), Bt, bcol, 0); STAGE(SA(0, 0), A, brow, 0);
;   STAGE(SB(0, 1), Bt, bcol + HALF, 0); STAGE(SA(0, 1), A, brow + HALF, 0);
;   if (wr == 1) BAR;
; __device__ __forceinline__ void gemm_phase(const Params& P, const GArgs& ga, int wid_s, int first, int stride) {
;     ...
;   for (int t = first; t < nitems; t += stride) {
;     const TileDesc td = get_tile(ga, t, nwg, nM, nN, nkt_all);
;     gemm_tile(P, ga, td, wid_s);
;     __syncthreads();
.Lnt_back:
	s_barrier
	v_readlane_b32 s0, v235, 0
	v_readlane_b32 s1, v235, 1
	v_readlane_b32 s4, v235, 2
	v_readlane_b32 s5, v235, 3
	v_readlane_b32 s6, v235, 4
	v_readlane_b32 s7, v235, 5
	v_readlane_b32 s8, v235, 6
	v_readlane_b32 s9, v235, 7
	v_readlane_b32 s15, v235, 8
	v_readlane_b32 s17, v235, 9
	v_readlane_b32 s38, v235, 10
	v_readlane_b32 s50, v235, 11
	v_readlane_b32 s51, v235, 12
	v_readlane_b32 s79, v235, 13
	v_readlane_b32 s84, v235, 14
	v_readlane_b32 s85, v235, 15
	v_readlane_b32 s86, v235, 16
	v_readlane_b32 s87, v235, 17
	v_readlane_b32 s92, v235, 18
	v_readlane_b32 s98, v235, 19
	v_readlane_b32 s99, v235, 20
	v_mov_b32_e32 v0, v200
	v_mov_b32_e32 v148, v232
	v_mov_b32_e32 v149, v233
	v_ashrrev_i32_e32 v24, 8, v0
	s_nop 1
	v_cmp_eq_u32_e32 vcc, 1, v24
	s_nop 4

; #define STAGE(PP, RSRC, br, kt) do { const int _so = ((br) * K + (kt) * BK) * 2; \
;       __builtin_amdgcn_raw_ptr_buffer_load_lds(RSRC, LDSP((char*)(PP) + ldsoff), 16, voff0, _so, 0, 0); \
;       __builtin_amdgcn_raw_ptr_buffer_load_lds(RSRC, LDSP((char*)(PP) + ldsoff + 8192), 16, voff1, _so, 0, 0); \
;     } while (0)
; #define LDB(dst, b, h) for (int n = 0; n < 2; ++n) for (int k = 0; k < 2; ++k) \
;     dst[n][k] = *reinterpret_cast<const bf16x8*>((char*)SB(b, h) + lds_byte(wc * 32 + n * 16 + fr, k * 32 + fq * 8))
; #define WAIT_V(n) asm volatile("s_waitcnt vmcnt(" #n ")" ::: "memory")
; #define BAR __builtin_amdgcn_s_barrier()
; __device__ __forceinline__ void gemm_tile(const Params& P, const GArgs& ga, const TileDesc& td, int wid_s) {
;     ...
;   WAIT_V(4); BAR;
;   STAGE(SB(1, 0), Bt, bcol, 1); STAGE(SA(1, 0), A, brow, 1); STAGE(SB(1, 1), Bt, bcol + HALF, 1);
;   WAIT_V(6); BAR;
;   LDB(B0, 0, 0);
.Lnt_304:
	s_or_b64 exec, exec, s[0:1]
	s_mov_b32 m0, s75
	s_bitset1_b32 s99, 7
	s_mov_b32 s6, s10
	s_mov_b32 s7, s11
	s_waitcnt vmcnt(36)
	s_barrier
	buffer_load_dwordx4 v148, s[4:7], s99 offen lds
	s_mov_b32 m0, s74
	s_bitset1_b32 s98, 7
	buffer_load_dwordx4 v149, s[4:7], s99 offen lds
	s_mov_b32 m0, s83
	s_bitset1_b32 s38, 7
	buffer_load_dwordx4 v148, s[8:11], s98 offen lds
	s_mov_b32 m0, s82
	v_and_b32_e32 v19, 15, v0
	buffer_load_dwordx4 v149, s[8:11], s98 offen lds
	s_mov_b32 m0, s69
	v_lshlrev_b32_e32 v3, 2, v0
	buffer_load_dwordx4 v148, s[4:7], s38 offen lds
	s_mov_b32 m0, s68
	v_and_b32_e32 v18, 48, v0
	buffer_load_dwordx4 v149, s[4:7], s38 offen lds
	v_lshlrev_b32_e32 v2, 6, v19
	v_and_b32_e32 v3, 32, v3
	v_bitop3_b32 v146, v2, v3, v18 bitop3:0x36
	s_add_i32 s0, 0, 0x10000
	v_lshlrev_b32_e32 v3, 6, v0
	v_add_u32_e32 v2, s0, v146
	v_and_b32_e32 v147, 0x3000, v3
	v_add_u32_e32 v162, v2, v147
	s_waitcnt vmcnt(38)
	s_barrier
	ds_read_b128 v[2:5], v162
	ds_read_b128 v[6:9], v162 offset:1024
	ds_read_b128 v[10:13], v162 offset:2048
	ds_read_b128 v[14:17], v162 offset:3072
	s_branch .Lnt_join

; #define STAGE(PP, RSRC, br, kt) do { const int _so = ((br) * K + (kt) * BK) * 2; \
;       __builtin_amdgcn_raw_ptr_buffer_load_lds(RSRC, LDSP((char*)(PP) + ldsoff), 16, voff0, _so, 0, 0); \
;       __builtin_amdgcn_raw_ptr_buffer_load_lds(RSRC, LDSP((char*)(PP) + ldsoff + 8192), 16, voff1, _so, 0, 0); \
;     } while (0)
; #define LDA(dst, b, h) for (int m = 0; m < 4; ++m) for (int k = 0; k < 2; ++k) \
;     dst[m][k] = *reinterpret_cast<const bf16x8*>((char*)SA(b, h) + lds_byte(wr * 64 + m * 16 + fr, k * 32 + fq * 8))
; __device__ __forceinline__ void gemm_tile(const Params& P, const GArgs& ga, const TileDesc& td, int wid_s) {
;     ...
;   for (int t = 0; t < nt - 2; t += 2) {
;     LDA(At, 0, 0); STAGE(SA(1, 1), A, brow + HALF, t + 1);
.Lnt_join:
	v_lshlrev_b32_e32 v20, 6, v24
	v_or_b32_e32 v21, v20, v19
	v_or_b32_e32 v27, 16, v20
	v_or_b32_e32 v26, 32, v20
	v_or_b32_e32 v25, 48, v20
	s_cmp_gt_u32 s17, 2
	s_mov_b64 s[0:1], -1
	v_lshlrev_b32_e32 v159, 13, v24
	v_lshlrev_b32_e32 v22, 6, v21
	v_lshlrev_b32_e32 v23, 2, v21
	v_or_b32_e32 v21, v27, v19
	v_lshlrev_b32_e32 v161, 7, v27
	v_or_b32_e32 v20, v26, v19
	v_lshlrev_b32_e32 v160, 7, v26
	v_or_b32_e32 v19, v25, v19
	v_lshlrev_b32_e32 v158, 7, v25
	s_cbranch_scc1 .LBB0_306
	v_lshlrev_b32_e32 v163, 13, v24
	v_and_b32_e32 v24, 0x3c0, v22
	s_waitcnt vmcnt(15)
	v_and_b32_e32 v28, 32, v23
	v_bitop3_b32 v150, v24, v28, v18 bitop3:0x36
	v_lshlrev_b32_e32 v24, 6, v21
	v_lshlrev_b32_e32 v28, 2, v21
	v_and_b32_e32 v24, 0x3c0, v24
	v_and_b32_e32 v28, 32, v28
	v_bitop3_b32 v152, v24, v28, v18 bitop3:0x36
	v_lshlrev_b32_e32 v164, 7, v27
	v_lshlrev_b32_e32 v24, 6, v20
	v_lshlrev_b32_e32 v27, 2, v20
	v_and_b32_e32 v24, 0x3c0, v24
	v_and_b32_e32 v27, 32, v27
	v_bitop3_b32 v154, v24, v27, v18 bitop3:0x36
	v_lshlrev_b32_e32 v165, 7, v26
	v_lshlrev_b32_e32 v24, 6, v19
	v_lshlrev_b32_e32 v26, 2, v19
	v_and_b32_e32 v24, 0x3c0, v24
	v_and_b32_e32 v26, 32, v26
	v_lshlrev_b32_e32 v166, 7, v25
	v_or_b32_e32 v151, 0x400, v163
	v_or_b32_e32 v153, 0x400, v164
	v_or_b32_e32 v155, 0x400, v165
	v_bitop3_b32 v156, v24, v26, v18 bitop3:0x36
	v_or_b32_e32 v157, 0x400, v166
	s_mov_b64 s[0:1], 0

; __device__ __forceinline__ TileDesc get_tile(const GArgs& ga, int t, int nwg, int nM, int nN, int nkt_all) {
;   TileDesc td; td.kt0 = 0; td.nkt = nkt_all; td.mode = ga.mode; td.sp = 0;
;   int pm, pn;
;   if (t < nwg) {
;     tile_coords(t, nM, nN, pm, pn);
;   } else {
;     const int j = t - nwg; td.sp = j & 7; const int tt = j >> 3;
;     pm = NP / BM + tt / nN; pn = tt % nN;
;     if (nkt_all == 88) { td.kt0 = td.sp < 4 ? td.sp * 12 : 48 + (td.sp - 4) * 10; td.nkt = td.sp < 4 ? 12 : 10; }
;     else { td.nkt = nkt_all >> 3; td.kt0 = td.sp * td.nkt; }
;     td.mode = M_PART;
;   }
.LBB0_313:
	s_or_b64 exec, exec, s[0:1]
	s_cmp_eq_u32 s79, 0
	s_cbranch_scc0 .Lgu_noload
	v_lshrrev_b32_e32 v162, 2, v200
	v_and_b32_e32 v163, 0xffffffc0, v162
	v_add_u32_e32 v163, s84, v163
	v_and_or_b32 v162, v162, 12, v163
	v_mov_b32_e32 v163, 0
	v_lshl_add_u64 v[164:165], v[162:163], 2, s[72:73]
	global_load_dwordx4 v[204:207], v[164:165], off
	global_load_dwordx4 v[208:211], v[164:165], off offset:64
	global_load_dwordx4 v[212:215], v[164:165], off offset:128
	global_load_dwordx4 v[216:219], v[164:165], off offset:192
	global_load_dwordx4 v[220:223], v[164:165], off offset:512
	global_load_dwordx4 v[224:227], v[164:165], off offset:576
	global_load_dwordx4 v[170:173], v[164:165], off offset:640
	global_load_dwordx4 v[174:177], v[164:165], off offset:704
.Lgu_noload:
	s_add_i32 s0, s59, s39
	s_cmp_lt_i32 s0, s91
	s_cbranch_scc1 .Lnt_do
	s_waitcnt vmcnt(0)
	s_branch .Lnt_skip
.Lnt_do:
	v_writelane_b32 v234, s0, 0
	v_writelane_b32 v234, s1, 1
	v_writelane_b32 v234, s4, 2
	v_writelane_b32 v234, s5, 3
	v_writelane_b32 v234, s6, 4
	v_writelane_b32 v234, s7, 5
	v_writelane_b32 v234, s8, 6
	v_writelane_b32 v234, s9, 7
	v_writelane_b32 v234, s15, 8
	v_writelane_b32 v234, s17, 9
	v_writelane_b32 v234, s38, 10
	v_writelane_b32 v234, s50, 11
	v_writelane_b32 v234, s51, 12
	v_writelane_b32 v234, s79, 13
	v_writelane_b32 v234, s84, 14
	v_writelane_b32 v234, s85, 15
	v_writelane_b32 v234, s86, 16
	v_writelane_b32 v234, s87, 17
	v_writelane_b32 v234, s92, 18
	v_writelane_b32 v234, s98, 19
	v_writelane_b32 v234, s99, 20
	s_add_i32 s59, s59, s39
	s_cmp_ge_i32 s59, s54
	s_mov_b64 s[0:1], -1
	s_cbranch_scc0 .Lnt_300
	s_sub_i32 s0, s59, s54
	s_lshr_b32 s5, s0, 3
	s_mul_hi_u32 s0, s5, s45
	s_mul_i32 s1, s0, s78
	s_sub_i32 s1, s5, s1
	s_and_b32 s87, s59, 7
	s_add_i32 s4, s0, 1
	s_sub_i32 s6, s1, s78
	s_cmp_ge_u32 s1, s78
	s_cselect_b32 s0, s4, s0
	s_cselect_b32 s1, s6, s1
	s_add_i32 s4, s0, 1
	s_cmp_ge_u32 s1, s78
	s_cselect_b32 s6, s4, s0
	s_mov_b64 s[0:1], -1
	s_and_b64 vcc, exec, s[34:35]
	s_cbranch_vccz .Lnt_294
	s_mul_i32 s4, s87, s42
	s_mov_b64 s[0:1], 0

; __device__ __forceinline__ float fdiv(float a, float b) { return a * __builtin_amdgcn_rcpf(b); }
; __device__ __forceinline__ void gemm_tile(const Params& P, const GArgs& ga, const TileDesc& td, int wid_s) {
;     ...
;   if (mode == M_GU) {
;     LOAD_RSV
;     unsigned* __restrict__ G = reinterpret_cast<unsigned*>(WSU(G) + (size_t)rbase * FF + (bcol >> 1) + (x4 >> 1));
;     static_for<32>([&](auto ic) __attribute__((always_inline)) {
;       EPI_IDX;
;       const float rs = rsv[idx];
;       float g0 = rs * acc[ai][0][m][0][j], u0 = rs * acc[ai][0][m][1][j];
;       float g1 = rs * acc[ai][1][m][0][j], u1 = rs * acc[ai][1][m][1][j];
;       __builtin_nontemporal_store(pack2(fdiv(g0 * u0, 1.f + __expf(-g0)), fdiv(g1 * u1, 1.f + __expf(-g1))), G + (size_t)rl * (FF / 2));
;       if constexpr ((idx & 7) == 7) __builtin_amdgcn_sched_barrier(0);
;     });
.LBB0_748:
	s_and_b64 vcc, exec, s[84:85]
	s_cbranch_vccz .LBB0_290
	v_and_b32_e32 v198, 15, v200
	v_and_b32_e32 v199, 0xc0, v200
	v_lshl_or_b32 v198, v198, 2, v199
	s_lshl_b32 s0, s15, 8
	v_mov_b32_e32 v199, 0x2c00
	v_mad_u32_u24 v198, v162, v199, v198
	v_mov_b32_e32 v199, s17
	v_add_u32_e32 v198, s0, v198
	s_waitcnt vmcnt(15)
	v_fmamk_f32 v204, v204, 0x3a000000, v199
	v_fmamk_f32 v205, v205, 0x3a000000, v199
	v_fmamk_f32 v206, v206, 0x3a000000, v199
	v_fmamk_f32 v207, v207, 0x3a000000, v199
	v_rsq_f32_e32 v130, v204
	v_rsq_f32_e32 v131, v205
	v_rsq_f32_e32 v132, v206
	v_rsq_f32_e32 v133, v207
	s_waitcnt vmcnt(14)
	v_fmamk_f32 v208, v208, 0x3a000000, v199
	v_fmamk_f32 v209, v209, 0x3a000000, v199
	v_fmamk_f32 v210, v210, 0x3a000000, v199
	v_fmamk_f32 v211, v211, 0x3a000000, v199
	v_rsq_f32_e32 v134, v208
	v_rsq_f32_e32 v135, v209
	v_rsq_f32_e32 v136, v210
	v_rsq_f32_e32 v137, v211
	v_mul_f32_e32 v130, 0xbfb8aa3b, v130
	v_mul_f32_e32 v131, 0xbfb8aa3b, v131
	v_mul_f32_e32 v132, 0xbfb8aa3b, v132
	v_mul_f32_e32 v133, 0xbfb8aa3b, v133
	s_waitcnt vmcnt(13)
	v_fmamk_f32 v212, v212, 0x3a000000, v199
	v_fmamk_f32 v213, v213, 0x3a000000, v199
	v_fmamk_f32 v214, v214, 0x3a000000, v199
	v_fmamk_f32 v215, v215, 0x3a000000, v199
	v_rsq_f32_e32 v138, v212
	v_rsq_f32_e32 v139, v213
	v_rsq_f32_e32 v140, v214
	v_rsq_f32_e32 v141, v215
	v_mul_f32_e32 v134, 0xbfb8aa3b, v134
	v_mul_f32_e32 v135, 0xbfb8aa3b, v135
	v_mul_f32_e32 v136, 0xbfb8aa3b, v136
	v_mul_f32_e32 v137, 0xbfb8aa3b, v137
	s_waitcnt vmcnt(12)
	v_fmamk_f32 v216, v216, 0x3a000000, v199
	v_fmamk_f32 v217, v217, 0x3a000000, v199
	v_fmamk_f32 v218, v218, 0x3a000000, v199
	v_fmamk_f32 v219, v219, 0x3a000000, v199
	v_rsq_f32_e32 v142, v216
	v_rsq_f32_e32 v143, v217
	v_rsq_f32_e32 v144, v218
	v_rsq_f32_e32 v145, v219
	v_mul_f32_e32 v138, 0xbfb8aa3b, v138
	v_mul_f32_e32 v139, 0xbfb8aa3b, v139
	v_mul_f32_e32 v140, 0xbfb8aa3b, v140
	v_mul_f32_e32 v141, 0xbfb8aa3b, v141
	s_waitcnt vmcnt(11)
	v_fmamk_f32 v220, v220, 0x3a000000, v199
	v_fmamk_f32 v221, v221, 0x3a000000, v199
	v_fmamk_f32 v222, v222, 0x3a000000, v199
	v_fmamk_f32 v223, v223, 0x3a000000, v199
	v_rsq_f32_e32 v146, v220
	v_rsq_f32_e32 v147, v221
	v_rsq_f32_e32 v148, v222
	v_rsq_f32_e32 v149, v223
	v_mul_f32_e32 v142, 0xbfb8aa3b, v142
	v_mul_f32_e32 v143, 0xbfb8aa3b, v143
	v_mul_f32_e32 v144, 0xbfb8aa3b, v144
	v_mul_f32_e32 v145, 0xbfb8aa3b, v145
	s_waitcnt vmcnt(10)
	v_fmamk_f32 v224, v224, 0x3a000000, v199
	v_fmamk_f32 v225, v225, 0x3a000000, v199
	v_fmamk_f32 v226, v226, 0x3a000000, v199
	v_fmamk_f32 v227, v227, 0x3a000000, v199
	v_rsq_f32_e32 v150, v224
	v_rsq_f32_e32 v151, v225
	v_rsq_f32_e32 v152, v226
	v_rsq_f32_e32 v153, v227
	v_mul_f32_e32 v146, 0xbfb8aa3b, v146
	v_mul_f32_e32 v147, 0xbfb8aa3b, v147
	v_mul_f32_e32 v148, 0xbfb8aa3b, v148
	v_mul_f32_e32 v149, 0xbfb8aa3b, v149
	s_waitcnt vmcnt(9)
	v_fmamk_f32 v170, v170, 0x3a000000, v199
	v_fmamk_f32 v171, v171, 0x3a000000, v199
	v_fmamk_f32 v172, v172, 0x3a000000, v199
	v_fmamk_f32 v173, v173, 0x3a000000, v199
	v_rsq_f32_e32 v154, v170
	v_rsq_f32_e32 v155, v171
	v_rsq_f32_e32 v156, v172
	v_rsq_f32_e32 v157, v173
	v_mul_f32_e32 v150, 0xbfb8aa3b, v150
	v_mul_f32_e32 v151, 0xbfb8aa3b, v151
	v_mul_f32_e32 v152, 0xbfb8aa3b, v152
	v_mul_f32_e32 v153, 0xbfb8aa3b, v153
	s_waitcnt vmcnt(8)
	v_fmamk_f32 v174, v174, 0x3a000000, v199
	v_fmamk_f32 v175, v175, 0x3a000000, v199
	v_fmamk_f32 v176, v176, 0x3a000000, v199
	v_fmamk_f32 v177, v177, 0x3a000000, v199
	v_rsq_f32_e32 v158, v174
	v_rsq_f32_e32 v159, v175
	v_rsq_f32_e32 v160, v176
	v_rsq_f32_e32 v161, v177
	v_mul_f32_e32 v154, 0xbfb8aa3b, v154
	v_mul_f32_e32 v155, 0xbfb8aa3b, v155
	v_mul_f32_e32 v156, 0xbfb8aa3b, v156
	v_mul_f32_e32 v157, 0xbfb8aa3b, v157
	s_nop 0
	v_mul_f32_e32 v158, 0xbfb8aa3b, v158
	v_mul_f32_e32 v159, 0xbfb8aa3b, v159
	v_mul_f32_e32 v160, 0xbfb8aa3b, v160
	v_mul_f32_e32 v161, 0xbfb8aa3b, v161
	v_mul_f32_e32 v178, v114, v130
	v_mul_f32_e32 v179, v126, v130
	v_mul_f32_e32 v180, v115, v131
	v_mul_f32_e32 v181, v127, v131
	v_mul_f32_e32 v182, v116, v132
	v_mul_f32_e32 v183, v128, v132
	v_mul_f32_e32 v184, v117, v133
	v_mul_f32_e32 v185, v129, v133
	v_exp_f32_e32 v178, v178
	v_exp_f32_e32 v179, v179
	v_exp_f32_e32 v180, v180
	v_exp_f32_e32 v181, v181
	v_exp_f32_e32 v182, v182
	v_exp_f32_e32 v183, v183
	v_exp_f32_e32 v184, v184
	v_exp_f32_e32 v185, v185
	v_mul_f32_e32 v186, v114, v118
	v_mul_f32_e32 v187, v126, v122
	v_mul_f32_e32 v188, v115, v119
	v_mul_f32_e32 v189, v127, v123
	v_mul_f32_e32 v190, v116, v120
	v_mul_f32_e32 v191, v128, v124
	v_mul_f32_e32 v192, v117, v121
	v_mul_f32_e32 v193, v129, v125
	v_fma_f32 v178, v178, v204, v204
	v_fma_f32 v179, v179, v204, v204
	v_fma_f32 v180, v180, v205, v205
	v_fma_f32 v181, v181, v205, v205
	v_fma_f32 v182, v182, v206, v206
	v_fma_f32 v183, v183, v206, v206
	v_fma_f32 v184, v184, v207, v207
	v_fma_f32 v185, v185, v207, v207
	v_rcp_f32_e32 v178, v178
	v_rcp_f32_e32 v179, v179
	v_rcp_f32_e32 v180, v180
	v_rcp_f32_e32 v181, v181
	v_rcp_f32_e32 v182, v182
	v_rcp_f32_e32 v183, v183
	v_rcp_f32_e32 v184, v184
	v_rcp_f32_e32 v185, v185
	v_mul_f32_e32 v186, v186, v178
	v_mul_f32_e32 v187, v187, v179
	v_mul_f32_e32 v188, v188, v180
	v_mul_f32_e32 v189, v189, v181
	s_add_u32 s4, s24, 0x0
	s_addc_u32 s5, s25, 0
	v_mul_f32_e32 v190, v190, v182
	v_mul_f32_e32 v191, v191, v183
	v_mul_f32_e32 v192, v192, v184
	v_mul_f32_e32 v193, v193, v185
	v_cvt_pk_bf16_f32 v194, v186, v187
	v_cvt_pk_bf16_f32 v195, v188, v189
	v_cvt_pk_bf16_f32 v196, v190, v191
	v_cvt_pk_bf16_f32 v197, v192, v193
	global_store_dword v198, v194, s[4:5] nt
	s_add_u32 s4, s4, 0x2c00
	s_addc_u32 s5, s5, 0
	global_store_dword v198, v195, s[4:5] nt
; __device__ __forceinline__ float fdiv(float a, float b) { return a * __builtin_amdgcn_rcpf(b); }
; __device__ __forceinline__ void gemm_tile(const Params& P, const GArgs& ga, const TileDesc& td, int wid_s) {
;     ...
;     static_for<32>([&](auto ic) __attribute__((always_inline)) {
;       EPI_IDX;
;       const float rs = rsv[idx];
;       float g0 = rs * acc[ai][0][m][0][j], u0 = rs * acc[ai][0][m][1][j];
;       float g1 = rs * acc[ai][1][m][0][j], u1 = rs * acc[ai][1][m][1][j];
;       __builtin_nontemporal_store(pack2(fdiv(g0 * u0, 1.f + __expf(-g0)), fdiv(g1 * u1, 1.f + __expf(-g1))), G + (size_t)rl * (FF / 2));
;       if constexpr ((idx & 7) == 7) __builtin_amdgcn_sched_barrier(0);
;     });
	s_add_u32 s4, s4, 0x2c00
	s_addc_u32 s5, s5, 0
	global_store_dword v198, v196, s[4:5] nt
	s_add_u32 s4, s4, 0x2c00
	s_addc_u32 s5, s5, 0
	global_store_dword v198, v197, s[4:5] nt
	v_mul_f32_e32 v178, v98, v134
	v_mul_f32_e32 v179, v110, v134
	v_mul_f32_e32 v180, v99, v135
	v_mul_f32_e32 v181, v111, v135
	v_mul_f32_e32 v182, v100, v136
	v_mul_f32_e32 v183, v112, v136
	v_mul_f32_e32 v184, v101, v137
	v_mul_f32_e32 v185, v113, v137
	v_exp_f32_e32 v178, v178
	v_exp_f32_e32 v179, v179
	v_exp_f32_e32 v180, v180
	v_exp_f32_e32 v181, v181
	v_exp_f32_e32 v182, v182
	v_exp_f32_e32 v183, v183
	v_exp_f32_e32 v184, v184
	v_exp_f32_e32 v185, v185
	v_mul_f32_e32 v186, v98, v102
	v_mul_f32_e32 v187, v110, v106
	v_mul_f32_e32 v188, v99, v103
	v_mul_f32_e32 v189, v111, v107
	v_mul_f32_e32 v190, v100, v104
	v_mul_f32_e32 v191, v112, v108
	v_mul_f32_e32 v192, v101, v105
	v_mul_f32_e32 v193, v113, v109
	v_fma_f32 v178, v178, v208, v208
	v_fma_f32 v179, v179, v208, v208
	v_fma_f32 v180, v180, v209, v209
	v_fma_f32 v181, v181, v209, v209
	v_fma_f32 v182, v182, v210, v210
	v_fma_f32 v183, v183, v210, v210
	v_fma_f32 v184, v184, v211, v211
	v_fma_f32 v185, v185, v211, v211
	v_rcp_f32_e32 v178, v178
	v_rcp_f32_e32 v179, v179
	v_rcp_f32_e32 v180, v180
	v_rcp_f32_e32 v181, v181
	v_rcp_f32_e32 v182, v182
	v_rcp_f32_e32 v183, v183
	v_rcp_f32_e32 v184, v184
	v_rcp_f32_e32 v185, v185
	v_mul_f32_e32 v186, v186, v178
	v_mul_f32_e32 v187, v187, v179
	v_mul_f32_e32 v188, v188, v180
	v_mul_f32_e32 v189, v189, v181
	s_add_u32 s4, s24, 0x2c000
	s_addc_u32 s5, s25, 0
	v_mul_f32_e32 v190, v190, v182
	v_mul_f32_e32 v191, v191, v183
	v_mul_f32_e32 v192, v192, v184
	v_mul_f32_e32 v193, v193, v185
	v_cvt_pk_bf16_f32 v194, v186, v187
	v_cvt_pk_bf16_f32 v195, v188, v189
	v_cvt_pk_bf16_f32 v196, v190, v191
	v_cvt_pk_bf16_f32 v197, v192, v193
	global_store_dword v198, v194, s[4:5] nt
	s_add_u32 s4, s4, 0x2c00
	s_addc_u32 s5, s5, 0
	global_store_dword v198, v195, s[4:5] nt
	s_add_u32 s4, s4, 0x2c00
	s_addc_u32 s5, s5, 0
	global_store_dword v198, v196, s[4:5] nt
	s_add_u32 s4, s4, 0x2c00
	s_addc_u32 s5, s5, 0
	global_store_dword v198, v197, s[4:5] nt
	v_mul_f32_e32 v178, v82, v138
	v_mul_f32_e32 v179, v94, v138
	v_mul_f32_e32 v180, v83, v139
	v_mul_f32_e32 v181, v95, v139
	v_mul_f32_e32 v182, v84, v140
	v_mul_f32_e32 v183, v96, v140
	v_mul_f32_e32 v184, v85, v141
	v_mul_f32_e32 v185, v97, v141
	v_exp_f32_e32 v178, v178
	v_exp_f32_e32 v179, v179
	v_exp_f32_e32 v180, v180
	v_exp_f32_e32 v181, v181
	v_exp_f32_e32 v182, v182
	v_exp_f32_e32 v183, v183
	v_exp_f32_e32 v184, v184
	v_exp_f32_e32 v185, v185
	v_mul_f32_e32 v186, v82, v86
	v_mul_f32_e32 v187, v94, v90
	v_mul_f32_e32 v188, v83, v87
	v_mul_f32_e32 v189, v95, v91
	v_mul_f32_e32 v190, v84, v88
	v_mul_f32_e32 v191, v96, v92
	v_mul_f32_e32 v192, v85, v89
	v_mul_f32_e32 v193, v97, v93
	v_fma_f32 v178, v178, v212, v212
	v_fma_f32 v179, v179, v212, v212
	v_fma_f32 v180, v180, v213, v213
	v_fma_f32 v181, v181, v213, v213
	v_fma_f32 v182, v182, v214, v214
	v_fma_f32 v183, v183, v214, v214
	v_fma_f32 v184, v184, v215, v215
	v_fma_f32 v185, v185, v215, v215
	v_rcp_f32_e32 v178, v178
	v_rcp_f32_e32 v179, v179
	v_rcp_f32_e32 v180, v180
	v_rcp_f32_e32 v181, v181
	v_rcp_f32_e32 v182, v182
	v_rcp_f32_e32 v183, v183
	v_rcp_f32_e32 v184, v184
	v_rcp_f32_e32 v185, v185
	v_mul_f32_e32 v186, v186, v178
	v_mul_f32_e32 v187, v187, v179
	v_mul_f32_e32 v188, v188, v180
	v_mul_f32_e32 v189, v189, v181
	s_add_u32 s4, s24, 0x58000
	s_addc_u32 s5, s25, 0
	v_mul_f32_e32 v190, v190, v182
	v_mul_f32_e32 v191, v191, v183
	v_mul_f32_e32 v192, v192, v184
	v_mul_f32_e32 v193, v193, v185
	v_cvt_pk_bf16_f32 v194, v186, v187
	v_cvt_pk_bf16_f32 v195, v188, v189
	v_cvt_pk_bf16_f32 v196, v190, v191
	v_cvt_pk_bf16_f32 v197, v192, v193
	global_store_dword v198, v194, s[4:5] nt
	s_add_u32 s4, s4, 0x2c00
	s_addc_u32 s5, s5, 0
	global_store_dword v198, v195, s[4:5] nt
	s_add_u32 s4, s4, 0x2c00
	s_addc_u32 s5, s5, 0
	global_store_dword v198, v196, s[4:5] nt
	s_add_u32 s4, s4, 0x2c00
	s_addc_u32 s5, s5, 0
	global_store_dword v198, v197, s[4:5] nt
	v_mul_f32_e32 v178, v66, v142
	v_mul_f32_e32 v179, v78, v142
	v_mul_f32_e32 v180, v67, v143
	v_mul_f32_e32 v181, v79, v143
	v_mul_f32_e32 v182, v68, v144
	v_mul_f32_e32 v183, v80, v144
	v_mul_f32_e32 v184, v69, v145
	v_mul_f32_e32 v185, v81, v145
	v_exp_f32_e32 v178, v178
	v_exp_f32_e32 v179, v179
	v_exp_f32_e32 v180, v180
	v_exp_f32_e32 v181, v181
	v_exp_f32_e32 v182, v182
	v_exp_f32_e32 v183, v183
	v_exp_f32_e32 v184, v184
	v_exp_f32_e32 v185, v185
	v_mul_f32_e32 v186, v66, v70
	v_mul_f32_e32 v187, v78, v74
	v_mul_f32_e32 v188, v67, v71
	v_mul_f32_e32 v189, v79, v75
	v_mul_f32_e32 v190, v68, v72
	v_mul_f32_e32 v191, v80, v76
	v_mul_f32_e32 v192, v69, v73
	v_mul_f32_e32 v193, v81, v77
	v_fma_f32 v178, v178, v216, v216
	v_fma_f32 v179, v179, v216, v216
	v_fma_f32 v180, v180, v217, v217
	v_fma_f32 v181, v181, v217, v217
	v_fma_f32 v182, v182, v218, v218
	v_fma_f32 v183, v183, v218, v218
	v_fma_f32 v184, v184, v219, v219
	v_fma_f32 v185, v185, v219, v219
	v_rcp_f32_e32 v178, v178
	v_rcp_f32_e32 v179, v179
	v_rcp_f32_e32 v180, v180
	v_rcp_f32_e32 v181, v181
	v_rcp_f32_e32 v182, v182
	v_rcp_f32_e32 v183, v183
	v_rcp_f32_e32 v184, v184
	v_rcp_f32_e32 v185, v185
	v_mul_f32_e32 v186, v186, v178
	v_mul_f32_e32 v187, v187, v179
	v_mul_f32_e32 v188, v188, v180
	v_mul_f32_e32 v189, v189, v181
	s_add_u32 s4, s24, 0x84000
	s_addc_u32 s5, s25, 0
	v_mul_f32_e32 v190, v190, v182
	v_mul_f32_e32 v191, v191, v183
	v_mul_f32_e32 v192, v192, v184
	v_mul_f32_e32 v193, v193, v185
	v_cvt_pk_bf16_f32 v194, v186, v187
	v_cvt_pk_bf16_f32 v195, v188, v189
; __device__ __forceinline__ float fdiv(float a, float b) { return a * __builtin_amdgcn_rcpf(b); }
; __device__ __forceinline__ void gemm_tile(const Params& P, const GArgs& ga, const TileDesc& td, int wid_s) {
;     ...
;     static_for<32>([&](auto ic) __attribute__((always_inline)) {
;       EPI_IDX;
;       const float rs = rsv[idx];
;       float g0 = rs * acc[ai][0][m][0][j], u0 = rs * acc[ai][0][m][1][j];
;       float g1 = rs * acc[ai][1][m][0][j], u1 = rs * acc[ai][1][m][1][j];
;       __builtin_nontemporal_store(pack2(fdiv(g0 * u0, 1.f + __expf(-g0)), fdiv(g1 * u1, 1.f + __expf(-g1))), G + (size_t)rl * (FF / 2));
;       if constexpr ((idx & 7) == 7) __builtin_amdgcn_sched_barrier(0);
;     });
	v_cvt_pk_bf16_f32 v196, v190, v191
	v_cvt_pk_bf16_f32 v197, v192, v193
	global_store_dword v198, v194, s[4:5] nt
	s_add_u32 s4, s4, 0x2c00
	s_addc_u32 s5, s5, 0
	global_store_dword v198, v195, s[4:5] nt
	s_add_u32 s4, s4, 0x2c00
	s_addc_u32 s5, s5, 0
	global_store_dword v198, v196, s[4:5] nt
	s_add_u32 s4, s4, 0x2c00
	s_addc_u32 s5, s5, 0
	global_store_dword v198, v197, s[4:5] nt
	v_mul_f32_e32 v178, v50, v146
	v_mul_f32_e32 v179, v62, v146
	v_mul_f32_e32 v180, v51, v147
	v_mul_f32_e32 v181, v63, v147
	v_mul_f32_e32 v182, v52, v148
	v_mul_f32_e32 v183, v64, v148
	v_mul_f32_e32 v184, v53, v149
	v_mul_f32_e32 v185, v65, v149
	v_exp_f32_e32 v178, v178
	v_exp_f32_e32 v179, v179
	v_exp_f32_e32 v180, v180
	v_exp_f32_e32 v181, v181
	v_exp_f32_e32 v182, v182
	v_exp_f32_e32 v183, v183
	v_exp_f32_e32 v184, v184
	v_exp_f32_e32 v185, v185
	v_mul_f32_e32 v186, v50, v54
	v_mul_f32_e32 v187, v62, v58
	v_mul_f32_e32 v188, v51, v55
	v_mul_f32_e32 v189, v63, v59
	v_mul_f32_e32 v190, v52, v56
	v_mul_f32_e32 v191, v64, v60
	v_mul_f32_e32 v192, v53, v57
	v_mul_f32_e32 v193, v65, v61
	v_fma_f32 v178, v178, v220, v220
	v_fma_f32 v179, v179, v220, v220
	v_fma_f32 v180, v180, v221, v221
	v_fma_f32 v181, v181, v221, v221
	v_fma_f32 v182, v182, v222, v222
	v_fma_f32 v183, v183, v222, v222
	v_fma_f32 v184, v184, v223, v223
	v_fma_f32 v185, v185, v223, v223
	v_rcp_f32_e32 v178, v178
	v_rcp_f32_e32 v179, v179
	v_rcp_f32_e32 v180, v180
	v_rcp_f32_e32 v181, v181
	v_rcp_f32_e32 v182, v182
	v_rcp_f32_e32 v183, v183
	v_rcp_f32_e32 v184, v184
	v_rcp_f32_e32 v185, v185
	v_mul_f32_e32 v186, v186, v178
	v_mul_f32_e32 v187, v187, v179
	v_mul_f32_e32 v188, v188, v180
	v_mul_f32_e32 v189, v189, v181
	s_add_u32 s4, s24, 0x160000
	s_addc_u32 s5, s25, 0
	v_mul_f32_e32 v190, v190, v182
	v_mul_f32_e32 v191, v191, v183
	v_mul_f32_e32 v192, v192, v184
	v_mul_f32_e32 v193, v193, v185
	v_cvt_pk_bf16_f32 v194, v186, v187
	v_cvt_pk_bf16_f32 v195, v188, v189
	v_cvt_pk_bf16_f32 v196, v190, v191
	v_cvt_pk_bf16_f32 v197, v192, v193
	global_store_dword v198, v194, s[4:5] nt
	s_add_u32 s4, s4, 0x2c00
	s_addc_u32 s5, s5, 0
	global_store_dword v198, v195, s[4:5] nt
	s_add_u32 s4, s4, 0x2c00
	s_addc_u32 s5, s5, 0
	global_store_dword v198, v196, s[4:5] nt
	s_add_u32 s4, s4, 0x2c00
	s_addc_u32 s5, s5, 0
	global_store_dword v198, v197, s[4:5] nt
	v_mul_f32_e32 v178, v34, v150
	v_mul_f32_e32 v179, v46, v150
	v_mul_f32_e32 v180, v35, v151
	v_mul_f32_e32 v181, v47, v151
	v_mul_f32_e32 v182, v36, v152
	v_mul_f32_e32 v183, v48, v152
	v_mul_f32_e32 v184, v37, v153
	v_mul_f32_e32 v185, v49, v153
	v_exp_f32_e32 v178, v178
	v_exp_f32_e32 v179, v179
	v_exp_f32_e32 v180, v180
	v_exp_f32_e32 v181, v181
	v_exp_f32_e32 v182, v182
	v_exp_f32_e32 v183, v183
	v_exp_f32_e32 v184, v184
	v_exp_f32_e32 v185, v185
	v_mul_f32_e32 v186, v34, v38
	v_mul_f32_e32 v187, v46, v42
	v_mul_f32_e32 v188, v35, v39
	v_mul_f32_e32 v189, v47, v43
	v_mul_f32_e32 v190, v36, v40
	v_mul_f32_e32 v191, v48, v44
	v_mul_f32_e32 v192, v37, v41
	v_mul_f32_e32 v193, v49, v45
	v_fma_f32 v178, v178, v224, v224
	v_fma_f32 v179, v179, v224, v224
	v_fma_f32 v180, v180, v225, v225
	v_fma_f32 v181, v181, v225, v225
	v_fma_f32 v182, v182, v226, v226
	v_fma_f32 v183, v183, v226, v226
	v_fma_f32 v184, v184, v227, v227
	v_fma_f32 v185, v185, v227, v227
	v_rcp_f32_e32 v178, v178
	v_rcp_f32_e32 v179, v179
	v_rcp_f32_e32 v180, v180
	v_rcp_f32_e32 v181, v181
	v_rcp_f32_e32 v182, v182
	v_rcp_f32_e32 v183, v183
	v_rcp_f32_e32 v184, v184
	v_rcp_f32_e32 v185, v185
	v_mul_f32_e32 v186, v186, v178
	v_mul_f32_e32 v187, v187, v179
	v_mul_f32_e32 v188, v188, v180
	v_mul_f32_e32 v189, v189, v181
	s_add_u32 s4, s24, 0x18c000
	s_addc_u32 s5, s25, 0
	v_mul_f32_e32 v190, v190, v182
	v_mul_f32_e32 v191, v191, v183
	v_mul_f32_e32 v192, v192, v184
	v_mul_f32_e32 v193, v193, v185
	v_cvt_pk_bf16_f32 v194, v186, v187
	v_cvt_pk_bf16_f32 v195, v188, v189
	v_cvt_pk_bf16_f32 v196, v190, v191
	v_cvt_pk_bf16_f32 v197, v192, v193
	global_store_dword v198, v194, s[4:5] nt
	s_add_u32 s4, s4, 0x2c00
	s_addc_u32 s5, s5, 0
	global_store_dword v198, v195, s[4:5] nt
; __device__ __forceinline__ float fdiv(float a, float b) { return a * __builtin_amdgcn_rcpf(b); }
; __device__ __forceinline__ void gemm_tile(const Params& P, const GArgs& ga, const TileDesc& td, int wid_s) {
;     ...
;     static_for<32>([&](auto ic) __attribute__((always_inline)) {
;       EPI_IDX;
;       const float rs = rsv[idx];
;       float g0 = rs * acc[ai][0][m][0][j], u0 = rs * acc[ai][0][m][1][j];
;       float g1 = rs * acc[ai][1][m][0][j], u1 = rs * acc[ai][1][m][1][j];
;       __builtin_nontemporal_store(pack2(fdiv(g0 * u0, 1.f + __expf(-g0)), fdiv(g1 * u1, 1.f + __expf(-g1))), G + (size_t)rl * (FF / 2));
;       if constexpr ((idx & 7) == 7) __builtin_amdgcn_sched_barrier(0);
;     });
	s_add_u32 s4, s4, 0x2c00
	s_addc_u32 s5, s5, 0
	global_store_dword v198, v196, s[4:5] nt
	s_add_u32 s4, s4, 0x2c00
	s_addc_u32 s5, s5, 0
	global_store_dword v198, v197, s[4:5] nt
	v_mul_f32_e32 v178, v18, v154
	v_mul_f32_e32 v179, v30, v154
	v_mul_f32_e32 v180, v19, v155
	v_mul_f32_e32 v181, v31, v155
	v_mul_f32_e32 v182, v20, v156
	v_mul_f32_e32 v183, v32, v156
	v_mul_f32_e32 v184, v21, v157
	v_mul_f32_e32 v185, v33, v157
	v_exp_f32_e32 v178, v178
	v_exp_f32_e32 v179, v179
	v_exp_f32_e32 v180, v180
	v_exp_f32_e32 v181, v181
	v_exp_f32_e32 v182, v182
	v_exp_f32_e32 v183, v183
	v_exp_f32_e32 v184, v184
	v_exp_f32_e32 v185, v185
	v_mul_f32_e32 v186, v18, v22
	v_mul_f32_e32 v187, v30, v26
	v_mul_f32_e32 v188, v19, v23
	v_mul_f32_e32 v189, v31, v27
	v_mul_f32_e32 v190, v20, v24
	v_mul_f32_e32 v191, v32, v28
	v_mul_f32_e32 v192, v21, v25
	v_mul_f32_e32 v193, v33, v29
	v_fma_f32 v178, v178, v170, v170
	v_fma_f32 v179, v179, v170, v170
	v_fma_f32 v180, v180, v171, v171
	v_fma_f32 v181, v181, v171, v171
	v_fma_f32 v182, v182, v172, v172
	v_fma_f32 v183, v183, v172, v172
	v_fma_f32 v184, v184, v173, v173
	v_fma_f32 v185, v185, v173, v173
	v_rcp_f32_e32 v178, v178
	v_rcp_f32_e32 v179, v179
	v_rcp_f32_e32 v180, v180
	v_rcp_f32_e32 v181, v181
	v_rcp_f32_e32 v182, v182
	v_rcp_f32_e32 v183, v183
	v_rcp_f32_e32 v184, v184
	v_rcp_f32_e32 v185, v185
	v_mul_f32_e32 v186, v186, v178
	v_mul_f32_e32 v187, v187, v179
	v_mul_f32_e32 v188, v188, v180
	v_mul_f32_e32 v189, v189, v181
	s_add_u32 s4, s24, 0x1b8000
	s_addc_u32 s5, s25, 0
	v_mul_f32_e32 v190, v190, v182
	v_mul_f32_e32 v191, v191, v183
	v_mul_f32_e32 v192, v192, v184
	v_mul_f32_e32 v193, v193, v185
	v_cvt_pk_bf16_f32 v194, v186, v187
	v_cvt_pk_bf16_f32 v195, v188, v189
	v_cvt_pk_bf16_f32 v196, v190, v191
	v_cvt_pk_bf16_f32 v197, v192, v193
	global_store_dword v198, v194, s[4:5] nt
	s_add_u32 s4, s4, 0x2c00
	s_addc_u32 s5, s5, 0
	global_store_dword v198, v195, s[4:5] nt
	s_add_u32 s4, s4, 0x2c00
	s_addc_u32 s5, s5, 0
	global_store_dword v198, v196, s[4:5] nt
	s_add_u32 s4, s4, 0x2c00
	s_addc_u32 s5, s5, 0
	global_store_dword v198, v197, s[4:5] nt
	v_mul_f32_e32 v178, v2, v158
	v_mul_f32_e32 v179, v14, v158
	v_mul_f32_e32 v180, v3, v159
	v_mul_f32_e32 v181, v15, v159
	v_mul_f32_e32 v182, v4, v160
	v_mul_f32_e32 v183, v16, v160
	v_mul_f32_e32 v184, v5, v161
	v_mul_f32_e32 v185, v17, v161
	v_exp_f32_e32 v178, v178
	v_exp_f32_e32 v179, v179
	v_exp_f32_e32 v180, v180
	v_exp_f32_e32 v181, v181
	v_exp_f32_e32 v182, v182
	v_exp_f32_e32 v183, v183
	v_exp_f32_e32 v184, v184
	v_exp_f32_e32 v185, v185
	v_mul_f32_e32 v186, v2, v6
	v_mul_f32_e32 v187, v14, v10
	v_mul_f32_e32 v188, v3, v7
	v_mul_f32_e32 v189, v15, v11
	v_mul_f32_e32 v190, v4, v8
	v_mul_f32_e32 v191, v16, v12
	v_mul_f32_e32 v192, v5, v9
	v_mul_f32_e32 v193, v17, v13
	v_fma_f32 v178, v178, v174, v174
	v_fma_f32 v179, v179, v174, v174
	v_fma_f32 v180, v180, v175, v175
	v_fma_f32 v181, v181, v175, v175
	v_fma_f32 v182, v182, v176, v176
	v_fma_f32 v183, v183, v176, v176
	v_fma_f32 v184, v184, v177, v177
	v_fma_f32 v185, v185, v177, v177
	v_rcp_f32_e32 v178, v178
	v_rcp_f32_e32 v179, v179
	v_rcp_f32_e32 v180, v180
	v_rcp_f32_e32 v181, v181
	v_rcp_f32_e32 v182, v182
	v_rcp_f32_e32 v183, v183
	v_rcp_f32_e32 v184, v184
	v_rcp_f32_e32 v185, v185
	v_mul_f32_e32 v186, v186, v178
	v_mul_f32_e32 v187, v187, v179
	v_mul_f32_e32 v188, v188, v180
	v_mul_f32_e32 v189, v189, v181
	s_add_u32 s4, s24, 0x1e4000
	s_addc_u32 s5, s25, 0
	v_mul_f32_e32 v190, v190, v182
	v_mul_f32_e32 v191, v191, v183
	v_mul_f32_e32 v192, v192, v184
	v_mul_f32_e32 v193, v193, v185
	v_cvt_pk_bf16_f32 v194, v186, v187
	v_cvt_pk_bf16_f32 v195, v188, v189
	v_cvt_pk_bf16_f32 v196, v190, v191
	v_cvt_pk_bf16_f32 v197, v192, v193
	global_store_dword v198, v194, s[4:5] nt
	s_add_u32 s4, s4, 0x2c00
	s_addc_u32 s5, s5, 0
	global_store_dword v198, v195, s[4:5] nt
	s_add_u32 s4, s4, 0x2c00
	s_addc_u32 s5, s5, 0
	global_store_dword v198, v196, s[4:5] nt
	s_add_u32 s4, s4, 0x2c00
	s_addc_u32 s5, s5, 0
	global_store_dword v198, v197, s[4:5] nt
	s_branch .LBB0_290
